# v047 + softmax row-sum reductions rewritten as v_pk_add trees over natural register pairs (16 ops instead of 51)
# speedup vs baseline: 1.0123x; 1.0032x over previous
; __device__ __forceinline__ unsigned cvtpk(float lo, float hi) { typedef __bf16 b2 __attribute__((ext_vector_type(2))); f32x2 v = {lo, hi}; b2 b = __builtin_convertvector(v, b2); return __builtin_bit_cast(unsigned, b); }
; __device__ __forceinline__ int crow(int r, int hi) { return (r & 3) + 8 * (r >> 2) + 4 * hi; }
; #define ATT_VREAD(dst, q_) do { const LAS char* vp_ = (const LAS char*)vb + (((q_) >> 1) * 32 + 16 * ((q_) & 1)) * VSTR; \
;         _Pragma("unroll") for (int d_ = 0; d_ < 4; ++d_) { dst[d_][0] = vtr(vp_ + voff[d_][0]); dst[d_][1] = vtr(vp_ + 8 * VSTR + voff[d_][1]); } } while (0)
;     ...
;         float rsa[4] = {0.f, 0.f, 0.f, 0.f};
; #pragma unroll
;         for (int r = 0; r < 16; ++r) { float p0 = __builtin_amdgcn_exp2f(s0[r] - mrun), p1 = __builtin_amdgcn_exp2f(s1[r] - mrun);
;             if (LAYER == 1) { const int kv = crow(r, hi); p0 = ((w0 >> kv) & 1u) ? p0 : 0.f; p1 = ((w1 >> kv) & 1u) ? p1 : 0.f; }
;             s0[r] = p0; s1[r] = p1; rsa[r & 3] += p0 + p1; }
;         lrun += (rsa[0] + rsa[1]) + (rsa[2] + rsa[3]);
; #pragma unroll
;         for (int s = 0; s < 2; ++s) {
;             v4u x; x.x = cvtpk(s0[8 * s + 0], s0[8 * s + 1]); x.y = cvtpk(s0[8 * s + 2], s0[8 * s + 3]); x.z = cvtpk(s0[8 * s + 4], s0[8 * s + 5]); x.w = cvtpk(s0[8 * s + 6], s0[8 * s + 7]); pb[0][s] = __builtin_bit_cast(bf16x8, x);
;             v4u y; y.x = cvtpk(s1[8 * s + 0], s1[8 * s + 1]); y.y = cvtpk(s1[8 * s + 2], s1[8 * s + 3]); y.z = cvtpk(s1[8 * s + 4], s1[8 * s + 5]); y.w = cvtpk(s1[8 * s + 6], s1[8 * s + 7]); pb[1][s] = __builtin_bit_cast(bf16x8, y); }
;     ...
;             if (wka) { vb = sa + KBUF + vlane; ATT_VREAD(vpre, 0); SM(wa0, wa1, a0, a1, pba);
;                 ATT_VREAD(va, 1); __builtin_amdgcn_s_setprio(1); ATT_PV(vpre, pba, 0); __builtin_amdgcn_s_setprio(0);
;                 ATT_VREAD(vbb, 2); __builtin_amdgcn_s_setprio(1); ATT_PV(va, pba, 1); __builtin_amdgcn_s_setprio(0);
;                 ATT_VREAD(va, 3); __builtin_amdgcn_s_setprio(1); ATT_PV(vbb, pba, 2); __builtin_amdgcn_s_setprio(0);
;                 __builtin_amdgcn_s_setprio(1); ATT_PV(va, pba, 3); __builtin_amdgcn_s_setprio(0); }
.LBB0_589:
	v_sub_f32_e32 v68, v68, v170
	v_sub_f32_e32 v100, v100, v170
	v_sub_f32_e32 v70, v70, v170
	v_sub_f32_e32 v102, v102, v170
	v_exp_f32_e32 v68, v68
	v_exp_f32_e32 v100, v100
	v_sub_f32_e32 v69, v69, v170
	v_sub_f32_e32 v101, v101, v170
	v_exp_f32_e32 v70, v70
	v_exp_f32_e32 v102, v102
	v_sub_f32_e32 v71, v71, v170
	v_sub_f32_e32 v103, v103, v170
	v_exp_f32_e32 v69, v69
	v_exp_f32_e32 v101, v101
	v_exp_f32_e32 v71, v71
	v_exp_f32_e32 v103, v103
	v_sub_f32_e32 v72, v72, v170
	v_sub_f32_e32 v104, v104, v170
	v_sub_f32_e32 v74, v74, v170
	v_sub_f32_e32 v106, v106, v170
	v_exp_f32_e32 v72, v72
	v_exp_f32_e32 v104, v104
	v_exp_f32_e32 v74, v74
	v_exp_f32_e32 v106, v106
	v_sub_f32_e32 v73, v73, v170
	v_sub_f32_e32 v105, v105, v170
	v_sub_f32_e32 v75, v75, v170
	v_sub_f32_e32 v107, v107, v170
	v_exp_f32_e32 v73, v73
	v_exp_f32_e32 v105, v105
	v_exp_f32_e32 v75, v75
	v_exp_f32_e32 v107, v107
	v_sub_f32_e32 v76, v76, v170
	v_sub_f32_e32 v108, v108, v170
	v_sub_f32_e32 v78, v78, v170
	v_sub_f32_e32 v110, v110, v170
	v_exp_f32_e32 v76, v76
	v_exp_f32_e32 v108, v108
	v_exp_f32_e32 v78, v78
	v_exp_f32_e32 v110, v110
	v_sub_f32_e32 v77, v77, v170
	v_sub_f32_e32 v109, v109, v170
	v_sub_f32_e32 v79, v79, v170
	v_sub_f32_e32 v111, v111, v170
	v_exp_f32_e32 v77, v77
	v_exp_f32_e32 v109, v109
	v_exp_f32_e32 v79, v79
	v_exp_f32_e32 v111, v111
	v_sub_f32_e32 v80, v80, v170
	v_sub_f32_e32 v112, v112, v170
	v_sub_f32_e32 v82, v82, v170
	v_sub_f32_e32 v114, v114, v170
	ds_read_b64_tr_b16 v[220:221], v200 offset:20480
	ds_read_b64_tr_b16 v[222:223], v201 offset:22528
	ds_read_b64_tr_b16 v[224:225], v202 offset:20480
	ds_read_b64_tr_b16 v[226:227], v203 offset:22528
	ds_read_b64_tr_b16 v[228:229], v204 offset:20480
	ds_read_b64_tr_b16 v[230:231], v205 offset:22528
	ds_read_b64_tr_b16 v[232:233], v206 offset:20480
	ds_read_b64_tr_b16 v[234:235], v207 offset:22528
	v_exp_f32_e32 v80, v80
	v_exp_f32_e32 v112, v112
	v_exp_f32_e32 v82, v82
	v_exp_f32_e32 v114, v114
	v_sub_f32_e32 v81, v81, v170
	v_sub_f32_e32 v113, v113, v170
	v_sub_f32_e32 v83, v83, v170
	v_sub_f32_e32 v115, v115, v170
	v_exp_f32_e32 v81, v81
	v_exp_f32_e32 v113, v113
	v_exp_f32_e32 v83, v83
	v_exp_f32_e32 v115, v115
	s_nop 0
	v_pk_add_f32 v[208:209], v[68:69], v[70:71]
	v_pk_add_f32 v[210:211], v[72:73], v[74:75]
	v_pk_add_f32 v[212:213], v[76:77], v[78:79]
	v_pk_add_f32 v[214:215], v[80:81], v[82:83]
	v_pk_add_f32 v[208:209], v[208:209], v[100:101]
	v_pk_add_f32 v[210:211], v[210:211], v[102:103]
	v_pk_add_f32 v[212:213], v[212:213], v[104:105]
	v_pk_add_f32 v[214:215], v[214:215], v[106:107]
	v_pk_add_f32 v[208:209], v[208:209], v[108:109]
	v_pk_add_f32 v[210:211], v[210:211], v[110:111]
	v_pk_add_f32 v[212:213], v[212:213], v[112:113]
	v_pk_add_f32 v[214:215], v[214:215], v[114:115]
	v_pk_add_f32 v[208:209], v[208:209], v[210:211]
	v_pk_add_f32 v[212:213], v[212:213], v[214:215]
	v_pk_add_f32 v[208:209], v[208:209], v[212:213]
	v_add_f32_e32 v240, v208, v209
	v_cvt_pk_bf16_f32 v214, v104, v105
	v_cvt_pk_bf16_f32 v212, v100, v101
	v_cvt_pk_bf16_f32 v210, v72, v73
	v_cvt_pk_bf16_f32 v208, v68, v69
	v_cvt_pk_bf16_f32 v209, v70, v71
	v_cvt_pk_bf16_f32 v211, v74, v75
	v_cvt_pk_bf16_f32 v213, v102, v103
	v_cvt_pk_bf16_f32 v215, v106, v107
	v_cvt_pk_bf16_f32 v216, v76, v77
	v_cvt_pk_bf16_f32 v217, v78, v79
	v_cvt_pk_bf16_f32 v218, v80, v81
	v_cvt_pk_bf16_f32 v219, v82, v83
	v_cvt_pk_bf16_f32 v236, v108, v109
	v_cvt_pk_bf16_f32 v237, v110, v111
	v_cvt_pk_bf16_f32 v238, v112, v113
	v_cvt_pk_bf16_f32 v239, v114, v115
	s_setprio 1
	s_waitcnt lgkmcnt(8)
	v_mfma_f32_32x32x16_bf16 v[52:67], v[152:155], v[208:211], v[52:67]
	v_add_f32_e32 v167, v167, v240
	v_mfma_f32_32x32x16_bf16 v[36:51], v[148:151], v[208:211], v[36:51]
	v_mfma_f32_32x32x16_bf16 v[20:35], v[160:163], v[208:211], v[20:35]
	v_mfma_f32_32x32x16_bf16 v[4:19], v[156:159], v[208:211], v[4:19]
	s_setprio 0
	ds_read_b64_tr_b16 v[148:149], v200 offset:24576
	ds_read_b64_tr_b16 v[150:151], v201 offset:26624
	ds_read_b64_tr_b16 v[152:153], v202 offset:24576
	ds_read_b64_tr_b16 v[154:155], v203 offset:26624
	ds_read_b64_tr_b16 v[156:157], v204 offset:24576
	ds_read_b64_tr_b16 v[158:159], v205 offset:26624
	ds_read_b64_tr_b16 v[160:161], v206 offset:24576
	ds_read_b64_tr_b16 v[162:163], v207 offset:26624
	s_setprio 1
	s_waitcnt lgkmcnt(14)
	v_mfma_f32_32x32x16_bf16 v[52:67], v[220:223], v[216:219], v[52:67]
	s_waitcnt lgkmcnt(12)
	v_mfma_f32_32x32x16_bf16 v[36:51], v[224:227], v[216:219], v[36:51]
	s_waitcnt lgkmcnt(10)
	v_mfma_f32_32x32x16_bf16 v[20:35], v[228:231], v[216:219], v[20:35]
	s_waitcnt lgkmcnt(8)
	v_mfma_f32_32x32x16_bf16 v[4:19], v[232:235], v[216:219], v[4:19]
	s_setprio 0
	ds_read_b64_tr_b16 v[208:209], v200 offset:28672
	ds_read_b64_tr_b16 v[210:211], v201 offset:30720
	ds_read_b64_tr_b16 v[216:217], v202 offset:28672
	ds_read_b64_tr_b16 v[218:219], v203 offset:30720
	ds_read_b64_tr_b16 v[220:221], v204 offset:28672
	ds_read_b64_tr_b16 v[222:223], v205 offset:30720
	ds_read_b64_tr_b16 v[224:225], v206 offset:28672
	ds_read_b64_tr_b16 v[226:227], v207 offset:30720
	s_setprio 1
	s_waitcnt lgkmcnt(14)
	v_mfma_f32_32x32x16_bf16 v[52:67], v[148:151], v[212:215], v[52:67]
	s_waitcnt lgkmcnt(12)
	v_mfma_f32_32x32x16_bf16 v[36:51], v[152:155], v[212:215], v[36:51]
	s_waitcnt lgkmcnt(10)
	v_mfma_f32_32x32x16_bf16 v[20:35], v[156:159], v[212:215], v[20:35]
	s_waitcnt lgkmcnt(8)
	v_mfma_f32_32x32x16_bf16 v[4:19], v[160:163], v[212:215], v[4:19]
	s_setprio 0
	s_setprio 1
	s_waitcnt lgkmcnt(6)
	v_mfma_f32_32x32x16_bf16 v[52:67], v[208:211], v[236:239], v[52:67]
	s_waitcnt lgkmcnt(4)
	v_mfma_f32_32x32x16_bf16 v[36:51], v[216:219], v[236:239], v[36:51]
	s_waitcnt lgkmcnt(2)
	v_mfma_f32_32x32x16_bf16 v[20:35], v[220:223], v[236:239], v[20:35]
	s_waitcnt lgkmcnt(0)
	v_mfma_f32_32x32x16_bf16 v[4:19], v[224:227], v[236:239], v[4:19]
	s_setprio 0

; __device__ __forceinline__ unsigned cvtpk(float lo, float hi) { typedef __bf16 b2 __attribute__((ext_vector_type(2))); f32x2 v = {lo, hi}; b2 b = __builtin_convertvector(v, b2); return __builtin_bit_cast(unsigned, b); }
; __device__ __forceinline__ int crow(int r, int hi) { return (r & 3) + 8 * (r >> 2) + 4 * hi; }
; #define ATT_VREAD(dst, q_) do { const LAS char* vp_ = (const LAS char*)vb + (((q_) >> 1) * 32 + 16 * ((q_) & 1)) * VSTR; \
;         _Pragma("unroll") for (int d_ = 0; d_ < 4; ++d_) { dst[d_][0] = vtr(vp_ + voff[d_][0]); dst[d_][1] = vtr(vp_ + 8 * VSTR + voff[d_][1]); } } while (0)
;     ...
;         float rsa[4] = {0.f, 0.f, 0.f, 0.f};
; #pragma unroll
;         for (int r = 0; r < 16; ++r) { float p0 = __builtin_amdgcn_exp2f(s0[r] - mrun), p1 = __builtin_amdgcn_exp2f(s1[r] - mrun);
;             if (LAYER == 1) { const int kv = crow(r, hi); p0 = ((w0 >> kv) & 1u) ? p0 : 0.f; p1 = ((w1 >> kv) & 1u) ? p1 : 0.f; }
;             s0[r] = p0; s1[r] = p1; rsa[r & 3] += p0 + p1; }
;         lrun += (rsa[0] + rsa[1]) + (rsa[2] + rsa[3]);
; #pragma unroll
;         for (int s = 0; s < 2; ++s) {
;             v4u x; x.x = cvtpk(s0[8 * s + 0], s0[8 * s + 1]); x.y = cvtpk(s0[8 * s + 2], s0[8 * s + 3]); x.z = cvtpk(s0[8 * s + 4], s0[8 * s + 5]); x.w = cvtpk(s0[8 * s + 6], s0[8 * s + 7]); pb[0][s] = __builtin_bit_cast(bf16x8, x);
;             v4u y; y.x = cvtpk(s1[8 * s + 0], s1[8 * s + 1]); y.y = cvtpk(s1[8 * s + 2], s1[8 * s + 3]); y.z = cvtpk(s1[8 * s + 4], s1[8 * s + 5]); y.w = cvtpk(s1[8 * s + 6], s1[8 * s + 7]); pb[1][s] = __builtin_bit_cast(bf16x8, y); }
;     ...
;             if (wkb) { vb = sbb + KBUF + vlane; ATT_VREAD(vpre, 0); SM(wb0, wb1, b0, b1, pbb);
;                 ATT_VREAD(va, 1); __builtin_amdgcn_s_setprio(1); ATT_PV(vpre, pbb, 0); __builtin_amdgcn_s_setprio(0);
;                 ATT_VREAD(vbb, 2); __builtin_amdgcn_s_setprio(1); ATT_PV(va, pbb, 1); __builtin_amdgcn_s_setprio(0);
;                 ATT_VREAD(va, 3); __builtin_amdgcn_s_setprio(1); ATT_PV(vbb, pbb, 2); __builtin_amdgcn_s_setprio(0);
;                 __builtin_amdgcn_s_setprio(1); ATT_PV(va, pbb, 3); __builtin_amdgcn_s_setprio(0); }
.LBB0_593:
	v_sub_f32_e32 v84, v84, v170
	v_sub_f32_e32 v116, v116, v170
	v_sub_f32_e32 v86, v86, v170
	v_sub_f32_e32 v118, v118, v170
	v_exp_f32_e32 v84, v84
	v_exp_f32_e32 v116, v116
	v_sub_f32_e32 v85, v85, v170
	v_sub_f32_e32 v117, v117, v170
	v_exp_f32_e32 v86, v86
	v_exp_f32_e32 v118, v118
	v_sub_f32_e32 v87, v87, v170
	v_sub_f32_e32 v119, v119, v170
	v_exp_f32_e32 v85, v85
	v_exp_f32_e32 v117, v117
	v_exp_f32_e32 v87, v87
	v_exp_f32_e32 v119, v119
	v_sub_f32_e32 v88, v88, v170
	v_sub_f32_e32 v120, v120, v170
	v_sub_f32_e32 v90, v90, v170
	v_sub_f32_e32 v122, v122, v170
	v_exp_f32_e32 v88, v88
	v_exp_f32_e32 v120, v120
	v_exp_f32_e32 v90, v90
	v_exp_f32_e32 v122, v122
	v_sub_f32_e32 v89, v89, v170
	v_sub_f32_e32 v121, v121, v170
	v_sub_f32_e32 v91, v91, v170
	v_sub_f32_e32 v123, v123, v170
	v_exp_f32_e32 v89, v89
	v_exp_f32_e32 v121, v121
	v_exp_f32_e32 v91, v91
	v_exp_f32_e32 v123, v123
	v_sub_f32_e32 v92, v92, v170
	v_sub_f32_e32 v124, v124, v170
	v_sub_f32_e32 v94, v94, v170
	v_sub_f32_e32 v126, v126, v170
	v_exp_f32_e32 v92, v92
	v_exp_f32_e32 v124, v124
	v_exp_f32_e32 v94, v94
	v_exp_f32_e32 v126, v126
	v_sub_f32_e32 v93, v93, v170
	v_sub_f32_e32 v125, v125, v170
	v_sub_f32_e32 v95, v95, v170
	v_sub_f32_e32 v127, v127, v170
	v_exp_f32_e32 v93, v93
	v_exp_f32_e32 v125, v125
	v_exp_f32_e32 v95, v95
	v_exp_f32_e32 v127, v127
	v_sub_f32_e32 v96, v96, v170
	v_sub_f32_e32 v128, v128, v170
	v_sub_f32_e32 v98, v98, v170
	v_sub_f32_e32 v130, v130, v170
	ds_read_b64_tr_b16 v[220:221], v200 offset:53248
	ds_read_b64_tr_b16 v[222:223], v201 offset:55296
	ds_read_b64_tr_b16 v[224:225], v202 offset:53248
	ds_read_b64_tr_b16 v[226:227], v203 offset:55296
	ds_read_b64_tr_b16 v[228:229], v204 offset:53248
	ds_read_b64_tr_b16 v[230:231], v205 offset:55296
	ds_read_b64_tr_b16 v[232:233], v206 offset:53248
	ds_read_b64_tr_b16 v[234:235], v207 offset:55296
	v_exp_f32_e32 v96, v96
	v_exp_f32_e32 v128, v128
	v_exp_f32_e32 v98, v98
	v_exp_f32_e32 v130, v130
	v_sub_f32_e32 v97, v97, v170
	v_sub_f32_e32 v129, v129, v170
	v_sub_f32_e32 v99, v99, v170
	v_sub_f32_e32 v131, v131, v170
	v_exp_f32_e32 v97, v97
	v_exp_f32_e32 v129, v129
	v_exp_f32_e32 v99, v99
	v_exp_f32_e32 v131, v131
	s_nop 0
	v_pk_add_f32 v[208:209], v[84:85], v[86:87]
	v_pk_add_f32 v[210:211], v[88:89], v[90:91]
	v_pk_add_f32 v[212:213], v[92:93], v[94:95]
	v_pk_add_f32 v[214:215], v[96:97], v[98:99]
	v_pk_add_f32 v[208:209], v[208:209], v[116:117]
	v_pk_add_f32 v[210:211], v[210:211], v[118:119]
	v_pk_add_f32 v[212:213], v[212:213], v[120:121]
	v_pk_add_f32 v[214:215], v[214:215], v[122:123]
	v_pk_add_f32 v[208:209], v[208:209], v[124:125]
	v_pk_add_f32 v[210:211], v[210:211], v[126:127]
	v_pk_add_f32 v[212:213], v[212:213], v[128:129]
	v_pk_add_f32 v[214:215], v[214:215], v[130:131]
	v_pk_add_f32 v[208:209], v[208:209], v[210:211]
	v_pk_add_f32 v[212:213], v[212:213], v[214:215]
	v_pk_add_f32 v[208:209], v[208:209], v[212:213]
	v_add_f32_e32 v240, v208, v209
	v_cvt_pk_bf16_f32 v214, v120, v121
	v_cvt_pk_bf16_f32 v212, v116, v117
	v_cvt_pk_bf16_f32 v210, v88, v89
	v_cvt_pk_bf16_f32 v208, v84, v85
	v_cvt_pk_bf16_f32 v209, v86, v87
	v_cvt_pk_bf16_f32 v211, v90, v91
	v_cvt_pk_bf16_f32 v213, v118, v119
	v_cvt_pk_bf16_f32 v215, v122, v123
	v_cvt_pk_bf16_f32 v216, v92, v93
	v_cvt_pk_bf16_f32 v217, v94, v95
	v_cvt_pk_bf16_f32 v218, v96, v97
	v_cvt_pk_bf16_f32 v219, v98, v99
	v_cvt_pk_bf16_f32 v236, v124, v125
	v_cvt_pk_bf16_f32 v237, v126, v127
	v_cvt_pk_bf16_f32 v238, v128, v129
	v_cvt_pk_bf16_f32 v239, v130, v131
	s_setprio 1
	s_waitcnt lgkmcnt(8)
	v_mfma_f32_32x32x16_bf16 v[52:67], v[152:155], v[208:211], v[52:67]
	v_add_f32_e32 v167, v167, v240
	v_mfma_f32_32x32x16_bf16 v[36:51], v[148:151], v[208:211], v[36:51]
	v_mfma_f32_32x32x16_bf16 v[20:35], v[160:163], v[208:211], v[20:35]
	v_mfma_f32_32x32x16_bf16 v[4:19], v[156:159], v[208:211], v[4:19]
	s_setprio 0
	ds_read_b64_tr_b16 v[148:149], v200 offset:57344
	ds_read_b64_tr_b16 v[150:151], v201 offset:59392
	ds_read_b64_tr_b16 v[152:153], v202 offset:57344
	ds_read_b64_tr_b16 v[154:155], v203 offset:59392
	ds_read_b64_tr_b16 v[156:157], v204 offset:57344
	ds_read_b64_tr_b16 v[158:159], v205 offset:59392
	ds_read_b64_tr_b16 v[160:161], v206 offset:57344
	ds_read_b64_tr_b16 v[162:163], v207 offset:59392
	s_setprio 1
	s_waitcnt lgkmcnt(14)
	v_mfma_f32_32x32x16_bf16 v[52:67], v[220:223], v[216:219], v[52:67]
	s_waitcnt lgkmcnt(12)
	v_mfma_f32_32x32x16_bf16 v[36:51], v[224:227], v[216:219], v[36:51]
	s_waitcnt lgkmcnt(10)
	v_mfma_f32_32x32x16_bf16 v[20:35], v[228:231], v[216:219], v[20:35]
	s_waitcnt lgkmcnt(8)
	v_mfma_f32_32x32x16_bf16 v[4:19], v[232:235], v[216:219], v[4:19]
	s_setprio 0
	ds_read_b64_tr_b16 v[208:209], v200 offset:61440
	ds_read_b64_tr_b16 v[210:211], v201 offset:63488
	ds_read_b64_tr_b16 v[200:201], v202 offset:61440
	ds_read_b64_tr_b16 v[202:203], v203 offset:63488
	ds_read_b64_tr_b16 v[216:217], v204 offset:61440
	ds_read_b64_tr_b16 v[218:219], v205 offset:63488
	ds_read_b64_tr_b16 v[204:205], v206 offset:61440
	ds_read_b64_tr_b16 v[206:207], v207 offset:63488
	s_setprio 1
	s_waitcnt lgkmcnt(14)
	v_mfma_f32_32x32x16_bf16 v[52:67], v[148:151], v[212:215], v[52:67]
	s_waitcnt lgkmcnt(12)
	v_mfma_f32_32x32x16_bf16 v[36:51], v[152:155], v[212:215], v[36:51]
	s_waitcnt lgkmcnt(10)
	v_mfma_f32_32x32x16_bf16 v[20:35], v[156:159], v[212:215], v[20:35]
	s_waitcnt lgkmcnt(8)
	v_mfma_f32_32x32x16_bf16 v[4:19], v[160:163], v[212:215], v[4:19]
	s_setprio 0
	s_setprio 1
	s_waitcnt lgkmcnt(6)
	v_mfma_f32_32x32x16_bf16 v[52:67], v[208:211], v[236:239], v[52:67]
	s_waitcnt lgkmcnt(4)
	v_mfma_f32_32x32x16_bf16 v[36:51], v[200:203], v[236:239], v[36:51]
	s_waitcnt lgkmcnt(2)
	v_mfma_f32_32x32x16_bf16 v[20:35], v[216:219], v[236:239], v[20:35]
	s_waitcnt lgkmcnt(0)
	v_mfma_f32_32x32x16_bf16 v[4:19], v[204:207], v[236:239], v[4:19]
	s_setprio 0

; __device__ __forceinline__ unsigned cvtpk(float lo, float hi) { typedef __bf16 b2 __attribute__((ext_vector_type(2))); f32x2 v = {lo, hi}; b2 b = __builtin_convertvector(v, b2); return __builtin_bit_cast(unsigned, b); }
; __device__ __forceinline__ int crow(int r, int hi) { return (r & 3) + 8 * (r >> 2) + 4 * hi; }
; #define ATT_VREAD(dst, q_) do { const LAS char* vp_ = (const LAS char*)vb + (((q_) >> 1) * 32 + 16 * ((q_) & 1)) * VSTR; \
;         _Pragma("unroll") for (int d_ = 0; d_ < 4; ++d_) { dst[d_][0] = vtr(vp_ + voff[d_][0]); dst[d_][1] = vtr(vp_ + 8 * VSTR + voff[d_][1]); } } while (0)
;     ...
;         float rsa[4] = {0.f, 0.f, 0.f, 0.f};
; #pragma unroll
;         for (int r = 0; r < 16; ++r) { float p0 = __builtin_amdgcn_exp2f(s0[r] - mrun), p1 = __builtin_amdgcn_exp2f(s1[r] - mrun);
;             if (LAYER == 1) { const int kv = crow(r, hi); p0 = ((w0 >> kv) & 1u) ? p0 : 0.f; p1 = ((w1 >> kv) & 1u) ? p1 : 0.f; }
;             s0[r] = p0; s1[r] = p1; rsa[r & 3] += p0 + p1; }
;         lrun += (rsa[0] + rsa[1]) + (rsa[2] + rsa[3]);
; #pragma unroll
;         for (int s = 0; s < 2; ++s) {
;             v4u x; x.x = cvtpk(s0[8 * s + 0], s0[8 * s + 1]); x.y = cvtpk(s0[8 * s + 2], s0[8 * s + 3]); x.z = cvtpk(s0[8 * s + 4], s0[8 * s + 5]); x.w = cvtpk(s0[8 * s + 6], s0[8 * s + 7]); pb[0][s] = __builtin_bit_cast(bf16x8, x);
;             v4u y; y.x = cvtpk(s1[8 * s + 0], s1[8 * s + 1]); y.y = cvtpk(s1[8 * s + 2], s1[8 * s + 3]); y.z = cvtpk(s1[8 * s + 4], s1[8 * s + 5]); y.w = cvtpk(s1[8 * s + 6], s1[8 * s + 7]); pb[1][s] = __builtin_bit_cast(bf16x8, y); }
;     ...
;             if (wka) { vb = sa + KBUF + vlane; ATT_VREAD(vpre, 0); SM(wa0, wa1, a0, a1, pba);
;                 ATT_VREAD(va, 1); __builtin_amdgcn_s_setprio(1); ATT_PV(vpre, pba, 0); __builtin_amdgcn_s_setprio(0);
;                 ATT_VREAD(vbb, 2); __builtin_amdgcn_s_setprio(1); ATT_PV(va, pba, 1); __builtin_amdgcn_s_setprio(0);
;                 ATT_VREAD(va, 3); __builtin_amdgcn_s_setprio(1); ATT_PV(vbb, pba, 2); __builtin_amdgcn_s_setprio(0);
;                 __builtin_amdgcn_s_setprio(1); ATT_PV(va, pba, 3); __builtin_amdgcn_s_setprio(0); }
.LBB0_3323:
	v_sub_f32_e32 v66, v66, v170
	v_sub_f32_e32 v98, v98, v170
	v_sub_f32_e32 v68, v68, v170
	v_sub_f32_e32 v100, v100, v170
	v_exp_f32_e32 v66, v66
	v_exp_f32_e32 v98, v98
	v_sub_f32_e32 v67, v67, v170
	v_sub_f32_e32 v99, v99, v170
	v_exp_f32_e32 v68, v68
	v_exp_f32_e32 v100, v100
	v_sub_f32_e32 v69, v69, v170
	v_sub_f32_e32 v101, v101, v170
	v_exp_f32_e32 v67, v67
	v_exp_f32_e32 v99, v99
	v_exp_f32_e32 v69, v69
	v_exp_f32_e32 v101, v101
	v_sub_f32_e32 v70, v70, v170
	v_sub_f32_e32 v102, v102, v170
	v_sub_f32_e32 v72, v72, v170
	v_sub_f32_e32 v104, v104, v170
	v_exp_f32_e32 v70, v70
	v_exp_f32_e32 v102, v102
	v_exp_f32_e32 v72, v72
	v_exp_f32_e32 v104, v104
	v_sub_f32_e32 v71, v71, v170
	v_sub_f32_e32 v103, v103, v170
	v_sub_f32_e32 v73, v73, v170
	v_sub_f32_e32 v105, v105, v170
	v_exp_f32_e32 v71, v71
	v_exp_f32_e32 v103, v103
	v_exp_f32_e32 v73, v73
	v_exp_f32_e32 v105, v105
	v_sub_f32_e32 v74, v74, v170
	v_sub_f32_e32 v106, v106, v170
	v_sub_f32_e32 v76, v76, v170
	v_sub_f32_e32 v108, v108, v170
	v_exp_f32_e32 v74, v74
	v_exp_f32_e32 v106, v106
	v_exp_f32_e32 v76, v76
	v_exp_f32_e32 v108, v108
	v_sub_f32_e32 v75, v75, v170
	v_sub_f32_e32 v107, v107, v170
	v_sub_f32_e32 v77, v77, v170
	v_sub_f32_e32 v109, v109, v170
	v_exp_f32_e32 v75, v75
	v_exp_f32_e32 v107, v107
	v_exp_f32_e32 v77, v77
	v_exp_f32_e32 v109, v109
	v_sub_f32_e32 v78, v78, v170
	v_sub_f32_e32 v110, v110, v170
	v_sub_f32_e32 v80, v80, v170
	v_sub_f32_e32 v112, v112, v170
	ds_read_b64_tr_b16 v[222:223], v201 offset:20480
	ds_read_b64_tr_b16 v[224:225], v202 offset:22528
	ds_read_b64_tr_b16 v[226:227], v203 offset:20480
	ds_read_b64_tr_b16 v[228:229], v204 offset:22528
	ds_read_b64_tr_b16 v[230:231], v205 offset:20480
	ds_read_b64_tr_b16 v[232:233], v206 offset:22528
	ds_read_b64_tr_b16 v[234:235], v207 offset:20480
	ds_read_b64_tr_b16 v[236:237], v208 offset:22528
	v_exp_f32_e32 v78, v78
	v_exp_f32_e32 v110, v110
	v_exp_f32_e32 v80, v80
	v_exp_f32_e32 v112, v112
	v_sub_f32_e32 v79, v79, v170
	v_sub_f32_e32 v111, v111, v170
	v_sub_f32_e32 v81, v81, v170
	v_sub_f32_e32 v113, v113, v170
	v_exp_f32_e32 v79, v79
	v_exp_f32_e32 v111, v111
	v_exp_f32_e32 v81, v81
	v_exp_f32_e32 v113, v113
	s_nop 0
	v_pk_add_f32 v[210:211], v[66:67], v[68:69]
	v_pk_add_f32 v[212:213], v[70:71], v[72:73]
	v_pk_add_f32 v[214:215], v[74:75], v[76:77]
	v_pk_add_f32 v[216:217], v[78:79], v[80:81]
	v_pk_add_f32 v[210:211], v[210:211], v[98:99]
	v_pk_add_f32 v[212:213], v[212:213], v[100:101]
	v_pk_add_f32 v[214:215], v[214:215], v[102:103]
	v_pk_add_f32 v[216:217], v[216:217], v[104:105]
	v_pk_add_f32 v[210:211], v[210:211], v[106:107]
	v_pk_add_f32 v[212:213], v[212:213], v[108:109]
	v_pk_add_f32 v[214:215], v[214:215], v[110:111]
	v_pk_add_f32 v[216:217], v[216:217], v[112:113]
	v_pk_add_f32 v[210:211], v[210:211], v[212:213]
	v_pk_add_f32 v[214:215], v[214:215], v[216:217]
	v_pk_add_f32 v[210:211], v[210:211], v[214:215]
	v_add_f32_e32 v209, v210, v211
	v_cvt_pk_bf16_f32 v216, v102, v103
	v_cvt_pk_bf16_f32 v214, v98, v99
	v_cvt_pk_bf16_f32 v212, v70, v71
	v_cvt_pk_bf16_f32 v210, v66, v67
	v_cvt_pk_bf16_f32 v211, v68, v69
	v_cvt_pk_bf16_f32 v213, v72, v73
	v_cvt_pk_bf16_f32 v215, v100, v101
	v_cvt_pk_bf16_f32 v217, v104, v105
	v_cvt_pk_bf16_f32 v218, v74, v75
	v_cvt_pk_bf16_f32 v219, v76, v77
	v_cvt_pk_bf16_f32 v220, v78, v79
	v_cvt_pk_bf16_f32 v221, v80, v81
	v_cvt_pk_bf16_f32 v238, v106, v107
	v_cvt_pk_bf16_f32 v239, v108, v109
	v_cvt_pk_bf16_f32 v240, v110, v111
	v_cvt_pk_bf16_f32 v241, v112, v113
	s_setprio 1
	s_waitcnt lgkmcnt(8)
	v_mfma_f32_32x32x16_bf16 v[50:65], v[150:153], v[210:213], v[50:65]
	v_add_f32_e32 v167, v167, v209
	v_mfma_f32_32x32x16_bf16 v[34:49], v[146:149], v[210:213], v[34:49]
	v_mfma_f32_32x32x16_bf16 v[18:33], v[158:161], v[210:213], v[18:33]
	v_mfma_f32_32x32x16_bf16 v[2:17], v[154:157], v[210:213], v[2:17]
	s_setprio 0
	ds_read_b64_tr_b16 v[146:147], v201 offset:24576
	ds_read_b64_tr_b16 v[148:149], v202 offset:26624
	ds_read_b64_tr_b16 v[150:151], v203 offset:24576
	ds_read_b64_tr_b16 v[152:153], v204 offset:26624
	ds_read_b64_tr_b16 v[154:155], v205 offset:24576
	ds_read_b64_tr_b16 v[156:157], v206 offset:26624
	ds_read_b64_tr_b16 v[158:159], v207 offset:24576
	ds_read_b64_tr_b16 v[160:161], v208 offset:26624
	s_setprio 1
	s_waitcnt lgkmcnt(14)
	v_mfma_f32_32x32x16_bf16 v[50:65], v[222:225], v[218:221], v[50:65]
	s_waitcnt lgkmcnt(12)
	v_mfma_f32_32x32x16_bf16 v[34:49], v[226:229], v[218:221], v[34:49]
	s_waitcnt lgkmcnt(10)
	v_mfma_f32_32x32x16_bf16 v[18:33], v[230:233], v[218:221], v[18:33]
	s_waitcnt lgkmcnt(8)
	v_mfma_f32_32x32x16_bf16 v[2:17], v[234:237], v[218:221], v[2:17]
	s_setprio 0
	ds_read_b64_tr_b16 v[210:211], v201 offset:28672
	ds_read_b64_tr_b16 v[212:213], v202 offset:30720
	ds_read_b64_tr_b16 v[218:219], v203 offset:28672
	ds_read_b64_tr_b16 v[220:221], v204 offset:30720
	ds_read_b64_tr_b16 v[222:223], v205 offset:28672
	ds_read_b64_tr_b16 v[224:225], v206 offset:30720
	ds_read_b64_tr_b16 v[226:227], v207 offset:28672
	ds_read_b64_tr_b16 v[228:229], v208 offset:30720
	s_setprio 1
	s_waitcnt lgkmcnt(14)
	v_mfma_f32_32x32x16_bf16 v[50:65], v[146:149], v[214:217], v[50:65]
	s_waitcnt lgkmcnt(12)
	v_mfma_f32_32x32x16_bf16 v[34:49], v[150:153], v[214:217], v[34:49]
	s_waitcnt lgkmcnt(10)
	v_mfma_f32_32x32x16_bf16 v[18:33], v[154:157], v[214:217], v[18:33]
	s_waitcnt lgkmcnt(8)
	v_mfma_f32_32x32x16_bf16 v[2:17], v[158:161], v[214:217], v[2:17]
	s_setprio 0
	s_setprio 1
	s_waitcnt lgkmcnt(6)
	v_mfma_f32_32x32x16_bf16 v[50:65], v[210:213], v[238:241], v[50:65]
	s_waitcnt lgkmcnt(4)
	v_mfma_f32_32x32x16_bf16 v[34:49], v[218:221], v[238:241], v[34:49]
	s_waitcnt lgkmcnt(2)
	v_mfma_f32_32x32x16_bf16 v[18:33], v[222:225], v[238:241], v[18:33]
	s_waitcnt lgkmcnt(0)
	v_mfma_f32_32x32x16_bf16 v[2:17], v[226:229], v[238:241], v[2:17]
	s_setprio 0

; __device__ __forceinline__ unsigned cvtpk(float lo, float hi) { typedef __bf16 b2 __attribute__((ext_vector_type(2))); f32x2 v = {lo, hi}; b2 b = __builtin_convertvector(v, b2); return __builtin_bit_cast(unsigned, b); }
; __device__ __forceinline__ int crow(int r, int hi) { return (r & 3) + 8 * (r >> 2) + 4 * hi; }
; #define ATT_VREAD(dst, q_) do { const LAS char* vp_ = (const LAS char*)vb + (((q_) >> 1) * 32 + 16 * ((q_) & 1)) * VSTR; \
;         _Pragma("unroll") for (int d_ = 0; d_ < 4; ++d_) { dst[d_][0] = vtr(vp_ + voff[d_][0]); dst[d_][1] = vtr(vp_ + 8 * VSTR + voff[d_][1]); } } while (0)
;     ...
;         float rsa[4] = {0.f, 0.f, 0.f, 0.f};
; #pragma unroll
;         for (int r = 0; r < 16; ++r) { float p0 = __builtin_amdgcn_exp2f(s0[r] - mrun), p1 = __builtin_amdgcn_exp2f(s1[r] - mrun);
;             if (LAYER == 1) { const int kv = crow(r, hi); p0 = ((w0 >> kv) & 1u) ? p0 : 0.f; p1 = ((w1 >> kv) & 1u) ? p1 : 0.f; }
;             s0[r] = p0; s1[r] = p1; rsa[r & 3] += p0 + p1; }
;         lrun += (rsa[0] + rsa[1]) + (rsa[2] + rsa[3]);
; #pragma unroll
;         for (int s = 0; s < 2; ++s) {
;             v4u x; x.x = cvtpk(s0[8 * s + 0], s0[8 * s + 1]); x.y = cvtpk(s0[8 * s + 2], s0[8 * s + 3]); x.z = cvtpk(s0[8 * s + 4], s0[8 * s + 5]); x.w = cvtpk(s0[8 * s + 6], s0[8 * s + 7]); pb[0][s] = __builtin_bit_cast(bf16x8, x);
;             v4u y; y.x = cvtpk(s1[8 * s + 0], s1[8 * s + 1]); y.y = cvtpk(s1[8 * s + 2], s1[8 * s + 3]); y.z = cvtpk(s1[8 * s + 4], s1[8 * s + 5]); y.w = cvtpk(s1[8 * s + 6], s1[8 * s + 7]); pb[1][s] = __builtin_bit_cast(bf16x8, y); }
;     ...
;             if (wkb) { vb = sbb + KBUF + vlane; ATT_VREAD(vpre, 0); SM(wb0, wb1, b0, b1, pbb);
;                 ATT_VREAD(va, 1); __builtin_amdgcn_s_setprio(1); ATT_PV(vpre, pbb, 0); __builtin_amdgcn_s_setprio(0);
;                 ATT_VREAD(vbb, 2); __builtin_amdgcn_s_setprio(1); ATT_PV(va, pbb, 1); __builtin_amdgcn_s_setprio(0);
;                 ATT_VREAD(va, 3); __builtin_amdgcn_s_setprio(1); ATT_PV(vbb, pbb, 2); __builtin_amdgcn_s_setprio(0);
;                 __builtin_amdgcn_s_setprio(1); ATT_PV(va, pbb, 3); __builtin_amdgcn_s_setprio(0); }
.LBB0_3327:
	v_sub_f32_e32 v82, v82, v170
	v_sub_f32_e32 v114, v114, v170
	v_sub_f32_e32 v84, v84, v170
	v_sub_f32_e32 v116, v116, v170
	v_exp_f32_e32 v82, v82
	v_exp_f32_e32 v114, v114
	v_sub_f32_e32 v83, v83, v170
	v_sub_f32_e32 v115, v115, v170
	v_exp_f32_e32 v84, v84
	v_exp_f32_e32 v116, v116
	v_sub_f32_e32 v85, v85, v170
	v_sub_f32_e32 v117, v117, v170
	v_exp_f32_e32 v83, v83
	v_exp_f32_e32 v115, v115
	v_exp_f32_e32 v85, v85
	v_exp_f32_e32 v117, v117
	v_sub_f32_e32 v86, v86, v170
	v_sub_f32_e32 v118, v118, v170
	v_sub_f32_e32 v88, v88, v170
	v_sub_f32_e32 v120, v120, v170
	v_exp_f32_e32 v86, v86
	v_exp_f32_e32 v118, v118
	v_exp_f32_e32 v88, v88
	v_exp_f32_e32 v120, v120
	v_sub_f32_e32 v87, v87, v170
	v_sub_f32_e32 v119, v119, v170
	v_sub_f32_e32 v89, v89, v170
	v_sub_f32_e32 v121, v121, v170
	v_exp_f32_e32 v87, v87
	v_exp_f32_e32 v119, v119
	v_exp_f32_e32 v89, v89
	v_exp_f32_e32 v121, v121
	v_sub_f32_e32 v90, v90, v170
	v_sub_f32_e32 v122, v122, v170
	v_sub_f32_e32 v92, v92, v170
	v_sub_f32_e32 v124, v124, v170
	v_exp_f32_e32 v90, v90
	v_exp_f32_e32 v122, v122
	v_exp_f32_e32 v92, v92
	v_exp_f32_e32 v124, v124
	v_sub_f32_e32 v91, v91, v170
	v_sub_f32_e32 v123, v123, v170
	v_sub_f32_e32 v93, v93, v170
	v_sub_f32_e32 v125, v125, v170
	v_exp_f32_e32 v91, v91
	v_exp_f32_e32 v123, v123
	v_exp_f32_e32 v93, v93
	v_exp_f32_e32 v125, v125
	v_sub_f32_e32 v94, v94, v170
	v_sub_f32_e32 v126, v126, v170
	v_sub_f32_e32 v96, v96, v170
	v_sub_f32_e32 v128, v128, v170
	ds_read_b64_tr_b16 v[222:223], v201 offset:53248
	ds_read_b64_tr_b16 v[224:225], v202 offset:55296
	ds_read_b64_tr_b16 v[226:227], v203 offset:53248
	ds_read_b64_tr_b16 v[228:229], v204 offset:55296
	ds_read_b64_tr_b16 v[230:231], v205 offset:53248
	ds_read_b64_tr_b16 v[232:233], v206 offset:55296
	ds_read_b64_tr_b16 v[234:235], v207 offset:53248
	ds_read_b64_tr_b16 v[236:237], v208 offset:55296
	v_exp_f32_e32 v94, v94
	v_exp_f32_e32 v126, v126
	v_exp_f32_e32 v96, v96
	v_exp_f32_e32 v128, v128
	v_sub_f32_e32 v95, v95, v170
	v_sub_f32_e32 v127, v127, v170
	v_sub_f32_e32 v97, v97, v170
	v_sub_f32_e32 v129, v129, v170
	v_exp_f32_e32 v95, v95
	v_exp_f32_e32 v127, v127
	v_exp_f32_e32 v97, v97
	v_exp_f32_e32 v129, v129
	s_nop 0
	v_pk_add_f32 v[210:211], v[82:83], v[84:85]
	v_pk_add_f32 v[212:213], v[86:87], v[88:89]
	v_pk_add_f32 v[214:215], v[90:91], v[92:93]
	v_pk_add_f32 v[216:217], v[94:95], v[96:97]
	v_pk_add_f32 v[210:211], v[210:211], v[114:115]
	v_pk_add_f32 v[212:213], v[212:213], v[116:117]
	v_pk_add_f32 v[214:215], v[214:215], v[118:119]
	v_pk_add_f32 v[216:217], v[216:217], v[120:121]
	v_pk_add_f32 v[210:211], v[210:211], v[122:123]
	v_pk_add_f32 v[212:213], v[212:213], v[124:125]
	v_pk_add_f32 v[214:215], v[214:215], v[126:127]
	v_pk_add_f32 v[216:217], v[216:217], v[128:129]
	v_pk_add_f32 v[210:211], v[210:211], v[212:213]
	v_pk_add_f32 v[214:215], v[214:215], v[216:217]
	v_pk_add_f32 v[210:211], v[210:211], v[214:215]
	v_add_f32_e32 v209, v210, v211
	v_cvt_pk_bf16_f32 v216, v118, v119
	v_cvt_pk_bf16_f32 v214, v114, v115
	v_cvt_pk_bf16_f32 v212, v86, v87
	v_cvt_pk_bf16_f32 v210, v82, v83
	v_cvt_pk_bf16_f32 v211, v84, v85
	v_cvt_pk_bf16_f32 v213, v88, v89
	v_cvt_pk_bf16_f32 v215, v116, v117
	v_cvt_pk_bf16_f32 v217, v120, v121
	v_cvt_pk_bf16_f32 v218, v90, v91
	v_cvt_pk_bf16_f32 v219, v92, v93
	v_cvt_pk_bf16_f32 v220, v94, v95
	v_cvt_pk_bf16_f32 v221, v96, v97
	v_cvt_pk_bf16_f32 v238, v122, v123
	v_cvt_pk_bf16_f32 v239, v124, v125
	v_cvt_pk_bf16_f32 v240, v126, v127
	v_cvt_pk_bf16_f32 v241, v128, v129
	s_setprio 1
	s_waitcnt lgkmcnt(8)
	v_mfma_f32_32x32x16_bf16 v[50:65], v[150:153], v[210:213], v[50:65]
	v_add_f32_e32 v167, v167, v209
	v_mfma_f32_32x32x16_bf16 v[34:49], v[146:149], v[210:213], v[34:49]
	v_mfma_f32_32x32x16_bf16 v[18:33], v[158:161], v[210:213], v[18:33]
	v_mfma_f32_32x32x16_bf16 v[2:17], v[154:157], v[210:213], v[2:17]
	s_setprio 0
	ds_read_b64_tr_b16 v[146:147], v201 offset:57344
	ds_read_b64_tr_b16 v[148:149], v202 offset:59392
	ds_read_b64_tr_b16 v[150:151], v203 offset:57344
	ds_read_b64_tr_b16 v[152:153], v204 offset:59392
	ds_read_b64_tr_b16 v[154:155], v205 offset:57344
	ds_read_b64_tr_b16 v[156:157], v206 offset:59392
	ds_read_b64_tr_b16 v[158:159], v207 offset:57344
	ds_read_b64_tr_b16 v[160:161], v208 offset:59392
	s_setprio 1
	s_waitcnt lgkmcnt(14)
	v_mfma_f32_32x32x16_bf16 v[50:65], v[222:225], v[218:221], v[50:65]
	s_waitcnt lgkmcnt(12)
	v_mfma_f32_32x32x16_bf16 v[34:49], v[226:229], v[218:221], v[34:49]
	s_waitcnt lgkmcnt(10)
	v_mfma_f32_32x32x16_bf16 v[18:33], v[230:233], v[218:221], v[18:33]
	s_waitcnt lgkmcnt(8)
	v_mfma_f32_32x32x16_bf16 v[2:17], v[234:237], v[218:221], v[2:17]
	s_setprio 0
	ds_read_b64_tr_b16 v[210:211], v201 offset:61440
	ds_read_b64_tr_b16 v[212:213], v202 offset:63488
	ds_read_b64_tr_b16 v[218:219], v203 offset:61440
	ds_read_b64_tr_b16 v[220:221], v204 offset:63488
	ds_read_b64_tr_b16 v[202:203], v205 offset:61440
	ds_read_b64_tr_b16 v[204:205], v206 offset:63488
	ds_read_b64_tr_b16 v[206:207], v207 offset:61440
	ds_read_b64_tr_b16 v[208:209], v208 offset:63488
	s_setprio 1
	s_waitcnt lgkmcnt(14)
	v_mfma_f32_32x32x16_bf16 v[50:65], v[146:149], v[214:217], v[50:65]
	s_waitcnt lgkmcnt(12)
	v_mfma_f32_32x32x16_bf16 v[34:49], v[150:153], v[214:217], v[34:49]
	s_waitcnt lgkmcnt(10)
	v_mfma_f32_32x32x16_bf16 v[18:33], v[154:157], v[214:217], v[18:33]
	s_waitcnt lgkmcnt(8)
	v_mfma_f32_32x32x16_bf16 v[2:17], v[158:161], v[214:217], v[2:17]
	s_setprio 0
	s_setprio 1
	s_waitcnt lgkmcnt(6)
	v_mfma_f32_32x32x16_bf16 v[50:65], v[210:213], v[238:241], v[50:65]
	s_waitcnt lgkmcnt(4)
	v_mfma_f32_32x32x16_bf16 v[34:49], v[218:221], v[238:241], v[34:49]
	s_waitcnt lgkmcnt(2)
	v_mfma_f32_32x32x16_bf16 v[18:33], v[202:205], v[238:241], v[18:33]
	s_waitcnt lgkmcnt(0)
	v_mfma_f32_32x32x16_bf16 v[2:17], v[206:209], v[238:241], v[2:17]
	s_setprio 0
